# baseline (speedup 1.0000x reference)
; DEVI void deferred_conv(const Params& p, char* smem, const int which) {
;     ...
; #pragma unroll
;     for (int u = 0; u < DQ_GRAB; ++u) {
;       int t = base + u;
;       if (t < thi) {
;         if (t < DQ_WO) tconv_load(p.w_o, 4096, t, R[u]);
;         else if (t < DQ_WO + DQ_WUP) tconv_load(p.w_up, NUP, t - DQ_WO, R[u]);
;         else tconv_load(p.w_down, 4096, t - DQ_WO - DQ_WUP, R[u]);
;       }
;     }
.Ldcv0_sdn_pro:
	v_mad_u32_u24 v54, v55, s88, v56
	global_load_dwordx4 v[168:171], v54, s[68:69] nt
	s_add_u32 s68, s68, s70
	s_addc_u32 s69, s69, 0
	global_load_dwordx4 v[172:175], v54, s[68:69] nt
	s_add_u32 s68, s68, s70
	s_addc_u32 s69, s69, 0
	global_load_dwordx4 v[176:179], v54, s[68:69] nt
	s_add_u32 s68, s68, s70
	s_addc_u32 s69, s69, 0
	global_load_dwordx4 v[180:183], v54, s[68:69] nt
	s_mul_i32 s6, s70, 3
	s_sub_u32 s68, s68, s6
	s_subb_u32 s69, s69, 0
	s_add_u32 s68, s68, 0x200
	s_addc_u32 s69, s69, 0
	global_load_dwordx4 v[184:187], v54, s[68:69] nt
	s_add_u32 s68, s68, s70
	s_addc_u32 s69, s69, 0
	global_load_dwordx4 v[188:191], v54, s[68:69] nt
	s_add_u32 s68, s68, s70
	s_addc_u32 s69, s69, 0
	global_load_dwordx4 v[192:195], v54, s[68:69] nt
	s_add_u32 s68, s68, s70
	s_addc_u32 s69, s69, 0
	global_load_dwordx4 v[196:199], v54, s[68:69] nt
	s_mul_i32 s6, s70, 3
	s_sub_u32 s68, s68, s6
	s_subb_u32 s69, s69, 0
	s_add_u32 s68, s68, 0x200
	s_addc_u32 s69, s69, 0
	global_load_dwordx4 v[200:203], v54, s[68:69] nt
	s_add_u32 s68, s68, s70
	s_addc_u32 s69, s69, 0
	global_load_dwordx4 v[204:207], v54, s[68:69] nt
	s_add_u32 s68, s68, s70
	s_addc_u32 s69, s69, 0
	global_load_dwordx4 v[208:211], v54, s[68:69] nt
	s_add_u32 s68, s68, s70
	s_addc_u32 s69, s69, 0
	global_load_dwordx4 v[212:215], v54, s[68:69] nt
	s_mul_i32 s6, s70, 3
	s_sub_u32 s68, s68, s6
	s_subb_u32 s69, s69, 0
	s_add_u32 s68, s68, 0x200
	s_addc_u32 s69, s69, 0
	global_load_dwordx4 v[216:219], v54, s[68:69] nt
	s_add_u32 s68, s68, s70
	s_addc_u32 s69, s69, 0
	global_load_dwordx4 v[220:223], v54, s[68:69] nt
	s_add_u32 s68, s68, s70
	s_addc_u32 s69, s69, 0
	global_load_dwordx4 v[224:227], v54, s[68:69] nt
	s_add_u32 s68, s68, s70
	s_addc_u32 s69, s69, 0
	global_load_dwordx4 v[228:231], v54, s[68:69] nt
	s_mul_i32 s6, s70, 3
	s_sub_u32 s68, s68, s6
	s_subb_u32 s69, s69, 0
	s_add_u32 s68, s68, 0x200
	s_addc_u32 s69, s69, 0
	s_waitcnt vmcnt(0)

; DEVI unsigned pack2(float a, float b) { f32v2 v = {a, b}; return __builtin_bit_cast(unsigned, __builtin_convertvector(v, bf16v2)); }
; DEVI void lds_barrier() { asm volatile("s_waitcnt lgkmcnt(0)" ::: "memory"); __builtin_amdgcn_s_barrier(); asm volatile("" ::: "memory"); }
; DEVI void tconv_store(const TcPre& R, u16* __restrict__ Wt, int K, int N, int t, float* lds, bool perm) {
;   const int tid = threadIdx.x;
;   const int tnN = N / 128;
;   int tk = t / tnN, tn = t % tnN, k0 = tk * 64, n0 = tn * 128;
;   {
;     float* d = lds + (tid >> 5) * 129 + (tid & 31) * 4;
;     d[0] = R.a[0]; d[1] = R.a[1]; d[2] = R.a[2]; d[3] = R.a[3];
;     d[16 * 129] = R.b[0]; d[16 * 129 + 1] = R.b[1]; d[16 * 129 + 2] = R.b[2]; d[16 * 129 + 3] = R.b[3];
;     d[32 * 129] = R.c[0]; d[32 * 129 + 1] = R.c[1]; d[32 * 129 + 2] = R.c[2]; d[32 * 129 + 3] = R.c[3];
;     d[48 * 129] = R.d[0]; d[48 * 129 + 1] = R.d[1]; d[48 * 129 + 2] = R.d[2]; d[48 * 129 + 3] = R.d[3];
;   }
;   lds_barrier();
;   int n0p = !perm ? n0 : (n0 < DFF ? (n0 / 128) * 256 : ((n0 - DFF) / 128) * 256 + 128);
; #pragma unroll
;   for (int p = 0; p < 2; ++p) {
;     int item = p * 512 + tid, n = item >> 3, kg = item & 7;
;     const float* s = lds + (kg * 8) * 129 + n;
;     uint4 o;
;     o.x = pack2(s[0], s[129]); o.y = pack2(s[2 * 129], s[3 * 129]);
;     o.z = pack2(s[4 * 129], s[5 * 129]); o.w = pack2(s[6 * 129], s[7 * 129]);
;     *(uint4*)(Wt + (size_t)(n0p + n) * K + k0 + kg * 8) = o;
;   }
;   lds_barrier();
; }
.Ldcv0_npd_st0:
	s_add_u32 s72, s84, s6
	s_addc_u32 s73, s85, 0
	s_add_u32 s78, s72, 0x80000
	s_addc_u32 s79, s73, 0
	s_waitcnt vmcnt(20)
	ds_write2_b32 v58, v168, v169 offset1:1
	ds_write2_b32 v58, v170, v171 offset0:2 offset1:3
	ds_write2_b32 v59, v172, v173 offset1:1
	ds_write2_b32 v59, v174, v175 offset0:2 offset1:3
	ds_write2_b32 v60, v176, v177 offset1:1
	ds_write2_b32 v60, v178, v179 offset0:2 offset1:3
	ds_write2_b32 v61, v180, v181 offset1:1
	ds_write2_b32 v61, v182, v183 offset0:2 offset1:3
	global_load_dwordx4 v[168:171], v54, s[68:69] nt
	s_add_u32 s68, s68, s70
	s_addc_u32 s69, s69, 0
	global_load_dwordx4 v[172:175], v54, s[68:69] nt
	s_add_u32 s68, s68, s70
	s_addc_u32 s69, s69, 0
	global_load_dwordx4 v[176:179], v54, s[68:69] nt
	s_add_u32 s68, s68, s70
	s_addc_u32 s69, s69, 0
	global_load_dwordx4 v[180:183], v54, s[68:69] nt
	s_mul_i32 s6, s70, 3
	s_sub_u32 s68, s68, s6
	s_subb_u32 s69, s69, 0
	s_add_u32 s68, s68, 0x200
	s_addc_u32 s69, s69, 0
	s_waitcnt lgkmcnt(0)
	s_barrier
	ds_read2_b32 v[104:105], v66 offset1:129
	ds_read2_b32 v[106:107], v67 offset1:129
	ds_read2_b32 v[108:109], v68 offset1:129
	ds_read2_b32 v[110:111], v69 offset1:129
	ds_read2_b32 v[112:113], v70 offset1:129
	ds_read2_b32 v[114:115], v71 offset1:129
	ds_read2_b32 v[116:117], v72 offset1:129
	ds_read2_b32 v[118:119], v73 offset1:129
	s_waitcnt lgkmcnt(4)
	v_cvt_pk_bf16_f32 v120, v104, v105
	v_cvt_pk_bf16_f32 v121, v106, v107
	v_cvt_pk_bf16_f32 v122, v108, v109
	v_cvt_pk_bf16_f32 v123, v110, v111
	global_store_dwordx4 v57, v[120:123], s[72:73]
	s_waitcnt lgkmcnt(0)
	v_cvt_pk_bf16_f32 v124, v112, v113
	v_cvt_pk_bf16_f32 v125, v114, v115
	v_cvt_pk_bf16_f32 v126, v116, v117
	v_cvt_pk_bf16_f32 v127, v118, v119
	global_store_dwordx4 v57, v[124:127], s[78:79]
	s_add_u32 s6, s86, 1
	s_cmp_eq_u32 s87, 0
	s_cbranch_scc1 .Ldcv0_np_st1
	s_lshl_b32 s7, s6, 8
	s_sub_u32 s15, s7, 0x5580
	s_cmp_lt_u32 s6, 86
	s_cselect_b32 s6, s7, s15
	s_lshl_b32 s6, s6, 13
	s_branch .Ldcv0_npd_st1

; DEVI unsigned pack2(float a, float b) { f32v2 v = {a, b}; return __builtin_bit_cast(unsigned, __builtin_convertvector(v, bf16v2)); }
; DEVI void lds_barrier() { asm volatile("s_waitcnt lgkmcnt(0)" ::: "memory"); __builtin_amdgcn_s_barrier(); asm volatile("" ::: "memory"); }
; DEVI void tconv_store(const TcPre& R, u16* __restrict__ Wt, int K, int N, int t, float* lds, bool perm) {
;   const int tid = threadIdx.x;
;   const int tnN = N / 128;
;   int tk = t / tnN, tn = t % tnN, k0 = tk * 64, n0 = tn * 128;
;   {
;     float* d = lds + (tid >> 5) * 129 + (tid & 31) * 4;
;     d[0] = R.a[0]; d[1] = R.a[1]; d[2] = R.a[2]; d[3] = R.a[3];
;     d[16 * 129] = R.b[0]; d[16 * 129 + 1] = R.b[1]; d[16 * 129 + 2] = R.b[2]; d[16 * 129 + 3] = R.b[3];
;     d[32 * 129] = R.c[0]; d[32 * 129 + 1] = R.c[1]; d[32 * 129 + 2] = R.c[2]; d[32 * 129 + 3] = R.c[3];
;     d[48 * 129] = R.d[0]; d[48 * 129 + 1] = R.d[1]; d[48 * 129 + 2] = R.d[2]; d[48 * 129 + 3] = R.d[3];
;   }
;   lds_barrier();
;   int n0p = !perm ? n0 : (n0 < DFF ? (n0 / 128) * 256 : ((n0 - DFF) / 128) * 256 + 128);
; #pragma unroll
;   for (int p = 0; p < 2; ++p) {
;     int item = p * 512 + tid, n = item >> 3, kg = item & 7;
;     const float* s = lds + (kg * 8) * 129 + n;
;     uint4 o;
;     o.x = pack2(s[0], s[129]); o.y = pack2(s[2 * 129], s[3 * 129]);
;     o.z = pack2(s[4 * 129], s[5 * 129]); o.w = pack2(s[6 * 129], s[7 * 129]);
;     *(uint4*)(Wt + (size_t)(n0p + n) * K + k0 + kg * 8) = o;
;   }
;   lds_barrier();
; }
.Ldcv0_npd_st1:
	s_add_u32 s72, s84, s6
	s_addc_u32 s73, s85, 0
	s_add_u32 s78, s72, 0x80000
	s_addc_u32 s79, s73, 0
	s_waitcnt vmcnt(20)
	ds_write2_b32 v62, v184, v185 offset1:1
	ds_write2_b32 v62, v186, v187 offset0:2 offset1:3
	ds_write2_b32 v63, v188, v189 offset1:1
	ds_write2_b32 v63, v190, v191 offset0:2 offset1:3
	ds_write2_b32 v64, v192, v193 offset1:1
	ds_write2_b32 v64, v194, v195 offset0:2 offset1:3
	ds_write2_b32 v65, v196, v197 offset1:1
	ds_write2_b32 v65, v198, v199 offset0:2 offset1:3
	global_load_dwordx4 v[184:187], v54, s[68:69] nt
	s_add_u32 s68, s68, s70
	s_addc_u32 s69, s69, 0
	global_load_dwordx4 v[188:191], v54, s[68:69] nt
	s_add_u32 s68, s68, s70
	s_addc_u32 s69, s69, 0
	global_load_dwordx4 v[192:195], v54, s[68:69] nt
	s_add_u32 s68, s68, s70
	s_addc_u32 s69, s69, 0
	global_load_dwordx4 v[196:199], v54, s[68:69] nt
	s_mul_i32 s6, s70, 3
	s_sub_u32 s68, s68, s6
	s_subb_u32 s69, s69, 0
	s_add_u32 s68, s68, 0x200
	s_addc_u32 s69, s69, 0
	s_waitcnt lgkmcnt(0)
	s_barrier
	ds_read2_b32 v[104:105], v74 offset1:129
	ds_read2_b32 v[106:107], v75 offset1:129
	ds_read2_b32 v[108:109], v76 offset1:129
	ds_read2_b32 v[110:111], v77 offset1:129
	ds_read2_b32 v[112:113], v78 offset1:129
	ds_read2_b32 v[114:115], v79 offset1:129
	ds_read2_b32 v[116:117], v80 offset1:129
	ds_read2_b32 v[118:119], v81 offset1:129
	s_waitcnt lgkmcnt(4)
	v_cvt_pk_bf16_f32 v120, v104, v105
	v_cvt_pk_bf16_f32 v121, v106, v107
	v_cvt_pk_bf16_f32 v122, v108, v109
	v_cvt_pk_bf16_f32 v123, v110, v111
	global_store_dwordx4 v57, v[120:123], s[72:73]
	s_waitcnt lgkmcnt(0)
	v_cvt_pk_bf16_f32 v124, v112, v113
	v_cvt_pk_bf16_f32 v125, v114, v115
	v_cvt_pk_bf16_f32 v126, v116, v117
	v_cvt_pk_bf16_f32 v127, v118, v119
	global_store_dwordx4 v57, v[124:127], s[78:79]
	s_add_u32 s6, s86, 2
	s_cmp_eq_u32 s87, 0
	s_cbranch_scc1 .Ldcv0_np_st2
	s_lshl_b32 s7, s6, 8
	s_sub_u32 s15, s7, 0x5580
	s_cmp_lt_u32 s6, 86
	s_cselect_b32 s6, s7, s15
	s_lshl_b32 s6, s6, 13
	s_branch .Ldcv0_npd_st2

; DEVI unsigned pack2(float a, float b) { f32v2 v = {a, b}; return __builtin_bit_cast(unsigned, __builtin_convertvector(v, bf16v2)); }
; DEVI void lds_barrier() { asm volatile("s_waitcnt lgkmcnt(0)" ::: "memory"); __builtin_amdgcn_s_barrier(); asm volatile("" ::: "memory"); }
; DEVI void tconv_store(const TcPre& R, u16* __restrict__ Wt, int K, int N, int t, float* lds, bool perm) {
;   const int tid = threadIdx.x;
;   const int tnN = N / 128;
;   int tk = t / tnN, tn = t % tnN, k0 = tk * 64, n0 = tn * 128;
;   {
;     float* d = lds + (tid >> 5) * 129 + (tid & 31) * 4;
;     d[0] = R.a[0]; d[1] = R.a[1]; d[2] = R.a[2]; d[3] = R.a[3];
;     d[16 * 129] = R.b[0]; d[16 * 129 + 1] = R.b[1]; d[16 * 129 + 2] = R.b[2]; d[16 * 129 + 3] = R.b[3];
;     d[32 * 129] = R.c[0]; d[32 * 129 + 1] = R.c[1]; d[32 * 129 + 2] = R.c[2]; d[32 * 129 + 3] = R.c[3];
;     d[48 * 129] = R.d[0]; d[48 * 129 + 1] = R.d[1]; d[48 * 129 + 2] = R.d[2]; d[48 * 129 + 3] = R.d[3];
;   }
;   lds_barrier();
;   int n0p = !perm ? n0 : (n0 < DFF ? (n0 / 128) * 256 : ((n0 - DFF) / 128) * 256 + 128);
; #pragma unroll
;   for (int p = 0; p < 2; ++p) {
;     int item = p * 512 + tid, n = item >> 3, kg = item & 7;
;     const float* s = lds + (kg * 8) * 129 + n;
;     uint4 o;
;     o.x = pack2(s[0], s[129]); o.y = pack2(s[2 * 129], s[3 * 129]);
;     o.z = pack2(s[4 * 129], s[5 * 129]); o.w = pack2(s[6 * 129], s[7 * 129]);
;     *(uint4*)(Wt + (size_t)(n0p + n) * K + k0 + kg * 8) = o;
;   }
;   lds_barrier();
; }
.Ldcv0_npd_st2:
	s_add_u32 s72, s84, s6
	s_addc_u32 s73, s85, 0
	s_add_u32 s78, s72, 0x80000
	s_addc_u32 s79, s73, 0
	s_waitcnt vmcnt(20)
	ds_write2_b32 v58, v200, v201 offset1:1
	ds_write2_b32 v58, v202, v203 offset0:2 offset1:3
	ds_write2_b32 v59, v204, v205 offset1:1
	ds_write2_b32 v59, v206, v207 offset0:2 offset1:3
	ds_write2_b32 v60, v208, v209 offset1:1
	ds_write2_b32 v60, v210, v211 offset0:2 offset1:3
	ds_write2_b32 v61, v212, v213 offset1:1
	ds_write2_b32 v61, v214, v215 offset0:2 offset1:3
	global_load_dwordx4 v[200:203], v54, s[68:69] nt
	s_add_u32 s68, s68, s70
	s_addc_u32 s69, s69, 0
	global_load_dwordx4 v[204:207], v54, s[68:69] nt
	s_add_u32 s68, s68, s70
	s_addc_u32 s69, s69, 0
	global_load_dwordx4 v[208:211], v54, s[68:69] nt
	s_add_u32 s68, s68, s70
	s_addc_u32 s69, s69, 0
	global_load_dwordx4 v[212:215], v54, s[68:69] nt
	s_mul_i32 s6, s70, 3
	s_sub_u32 s68, s68, s6
	s_subb_u32 s69, s69, 0
	s_add_u32 s68, s68, 0x200
	s_addc_u32 s69, s69, 0
	s_waitcnt lgkmcnt(0)
	s_barrier
	ds_read2_b32 v[104:105], v66 offset1:129
	ds_read2_b32 v[106:107], v67 offset1:129
	ds_read2_b32 v[108:109], v68 offset1:129
	ds_read2_b32 v[110:111], v69 offset1:129
	ds_read2_b32 v[112:113], v70 offset1:129
	ds_read2_b32 v[114:115], v71 offset1:129
	ds_read2_b32 v[116:117], v72 offset1:129
	ds_read2_b32 v[118:119], v73 offset1:129
	s_waitcnt lgkmcnt(4)
	v_cvt_pk_bf16_f32 v120, v104, v105
	v_cvt_pk_bf16_f32 v121, v106, v107
	v_cvt_pk_bf16_f32 v122, v108, v109
	v_cvt_pk_bf16_f32 v123, v110, v111
	global_store_dwordx4 v57, v[120:123], s[72:73]
	s_waitcnt lgkmcnt(0)
	v_cvt_pk_bf16_f32 v124, v112, v113
	v_cvt_pk_bf16_f32 v125, v114, v115
	v_cvt_pk_bf16_f32 v126, v116, v117
	v_cvt_pk_bf16_f32 v127, v118, v119
	global_store_dwordx4 v57, v[124:127], s[78:79]
	s_add_u32 s6, s86, 3
	s_cmp_eq_u32 s87, 0
	s_cbranch_scc1 .Ldcv0_np_st3
	s_lshl_b32 s7, s6, 8
	s_sub_u32 s15, s7, 0x5580
	s_cmp_lt_u32 s6, 86
	s_cselect_b32 s6, s7, s15
	s_lshl_b32 s6, s6, 13
	s_branch .Ldcv0_npd_st3

; DEVI unsigned pack2(float a, float b) { f32v2 v = {a, b}; return __builtin_bit_cast(unsigned, __builtin_convertvector(v, bf16v2)); }
; DEVI void lds_barrier() { asm volatile("s_waitcnt lgkmcnt(0)" ::: "memory"); __builtin_amdgcn_s_barrier(); asm volatile("" ::: "memory"); }
; DEVI void tconv_store(const TcPre& R, u16* __restrict__ Wt, int K, int N, int t, float* lds, bool perm) {
;   const int tid = threadIdx.x;
;   const int tnN = N / 128;
;   int tk = t / tnN, tn = t % tnN, k0 = tk * 64, n0 = tn * 128;
;   {
;     float* d = lds + (tid >> 5) * 129 + (tid & 31) * 4;
;     d[0] = R.a[0]; d[1] = R.a[1]; d[2] = R.a[2]; d[3] = R.a[3];
;     d[16 * 129] = R.b[0]; d[16 * 129 + 1] = R.b[1]; d[16 * 129 + 2] = R.b[2]; d[16 * 129 + 3] = R.b[3];
;     d[32 * 129] = R.c[0]; d[32 * 129 + 1] = R.c[1]; d[32 * 129 + 2] = R.c[2]; d[32 * 129 + 3] = R.c[3];
;     d[48 * 129] = R.d[0]; d[48 * 129 + 1] = R.d[1]; d[48 * 129 + 2] = R.d[2]; d[48 * 129 + 3] = R.d[3];
;   }
;   lds_barrier();
;   int n0p = !perm ? n0 : (n0 < DFF ? (n0 / 128) * 256 : ((n0 - DFF) / 128) * 256 + 128);
; #pragma unroll
;   for (int p = 0; p < 2; ++p) {
;     int item = p * 512 + tid, n = item >> 3, kg = item & 7;
;     const float* s = lds + (kg * 8) * 129 + n;
;     uint4 o;
;     o.x = pack2(s[0], s[129]); o.y = pack2(s[2 * 129], s[3 * 129]);
;     o.z = pack2(s[4 * 129], s[5 * 129]); o.w = pack2(s[6 * 129], s[7 * 129]);
;     *(uint4*)(Wt + (size_t)(n0p + n) * K + k0 + kg * 8) = o;
;   }
;   lds_barrier();
; }
; DEVI void deferred_conv(const Params& p, char* smem, const int which) {
;     ...
;     if (threadIdx.x == 0) *qs = tlo + (int)atomicAdd(ctr, (unsigned)DQ_GRAB);
.Ldcv0_npd_st3:
	s_add_u32 s72, s84, s6
	s_addc_u32 s73, s85, 0
	s_add_u32 s78, s72, 0x80000
	s_addc_u32 s79, s73, 0
	s_waitcnt vmcnt(20)
	ds_write2_b32 v62, v216, v217 offset1:1
	ds_write2_b32 v62, v218, v219 offset0:2 offset1:3
	ds_write2_b32 v63, v220, v221 offset1:1
	ds_write2_b32 v63, v222, v223 offset0:2 offset1:3
	ds_write2_b32 v64, v224, v225 offset1:1
	ds_write2_b32 v64, v226, v227 offset0:2 offset1:3
	ds_write2_b32 v65, v228, v229 offset1:1
	ds_write2_b32 v65, v230, v231 offset0:2 offset1:3
	global_load_dwordx4 v[216:219], v54, s[68:69] nt
	s_add_u32 s68, s68, s70
	s_addc_u32 s69, s69, 0
	global_load_dwordx4 v[220:223], v54, s[68:69] nt
	s_add_u32 s68, s68, s70
	s_addc_u32 s69, s69, 0
	global_load_dwordx4 v[224:227], v54, s[68:69] nt
	s_add_u32 s68, s68, s70
	s_addc_u32 s69, s69, 0
	global_load_dwordx4 v[228:231], v54, s[68:69] nt
	s_mul_i32 s6, s70, 3
	s_sub_u32 s68, s68, s6
	s_subb_u32 s69, s69, 0
	s_add_u32 s68, s68, 0x200
	s_addc_u32 s69, s69, 0
	s_cmp_lg_u32 s33, 0
	s_cbranch_scc1 .Ldcv0_b_st
	s_mov_b64 exec, 1
	s_waitcnt vmcnt(22)
	ds_write_b32 v84, v52
	s_mov_b64 exec, s[76:77]

; DEVI void lds_barrier() { asm volatile("s_waitcnt lgkmcnt(0)" ::: "memory"); __builtin_amdgcn_s_barrier(); asm volatile("" ::: "memory"); }
; DEVI void deferred_conv(const Params& p, char* smem, const int which) {
;     ...
;   for (;;) {
;     if (threadIdx.x == 0) *qs = tlo + (int)atomicAdd(ctr, (unsigned)DQ_GRAB);
;     lds_barrier();
;     int base = *qs;
;     lds_barrier();
;     if (base >= thi) break;
;     TcPre R[DQ_GRAB];
; #pragma unroll
;     for (int u = 0; u < DQ_GRAB; ++u) {
;       int t = base + u;
;       if (t < thi) {
;         if (t < DQ_WO) tconv_load(p.w_o, 4096, t, R[u]);
;         else if (t < DQ_WO + DQ_WUP) tconv_load(p.w_up, NUP, t - DQ_WO, R[u]);
;         else tconv_load(p.w_down, 4096, t - DQ_WO - DQ_WUP, R[u]);
;       }
;     }
.Ldcv1_q0:
	s_waitcnt lgkmcnt(0)
	s_barrier
	ds_read_b64 v[82:83], v84
	s_waitcnt lgkmcnt(0)
	v_readfirstlane_b32 s3, v82
	v_readfirstlane_b32 s4, v83
	s_cmp_ge_u32 s3, 0x1580
	s_cbranch_scc1 .Ldcv1_done
	s_lshr_b32 s6, s3, 5
	s_and_b32 s7, s3, 31
	s_lshl_b32 s6, s6, 20
	s_lshl_b32 s7, s7, 9
	s_add_u32 s6, s6, s7
	s_add_u32 s68, s28, s6
	s_addc_u32 s69, s29, 0
	s_mov_b32 s70, 0x40000
	s_movk_i32 s88, 0x4000
	v_mad_u32_u24 v54, v55, s88, v56
	global_load_dwordx4 v[168:171], v54, s[68:69] nt
	s_add_u32 s68, s68, s70
	s_addc_u32 s69, s69, 0
	global_load_dwordx4 v[172:175], v54, s[68:69] nt
	s_add_u32 s68, s68, s70
	s_addc_u32 s69, s69, 0
	global_load_dwordx4 v[176:179], v54, s[68:69] nt
	s_add_u32 s68, s68, s70
	s_addc_u32 s69, s69, 0
	global_load_dwordx4 v[180:183], v54, s[68:69] nt
	s_mul_i32 s6, s70, 3
	s_sub_u32 s68, s68, s6
	s_subb_u32 s69, s69, 0
	s_add_u32 s68, s68, 0x200
	s_addc_u32 s69, s69, 0
	global_load_dwordx4 v[184:187], v54, s[68:69] nt
	s_add_u32 s68, s68, s70
	s_addc_u32 s69, s69, 0
	global_load_dwordx4 v[188:191], v54, s[68:69] nt
	s_add_u32 s68, s68, s70
	s_addc_u32 s69, s69, 0
	global_load_dwordx4 v[192:195], v54, s[68:69] nt
	s_add_u32 s68, s68, s70
	s_addc_u32 s69, s69, 0
	global_load_dwordx4 v[196:199], v54, s[68:69] nt
	s_mul_i32 s6, s70, 3
	s_sub_u32 s68, s68, s6
	s_subb_u32 s69, s69, 0
	s_add_u32 s68, s68, 0x200
	s_addc_u32 s69, s69, 0
	global_load_dwordx4 v[200:203], v54, s[68:69] nt
	s_add_u32 s68, s68, s70
	s_addc_u32 s69, s69, 0
	global_load_dwordx4 v[204:207], v54, s[68:69] nt
	s_add_u32 s68, s68, s70
	s_addc_u32 s69, s69, 0
	global_load_dwordx4 v[208:211], v54, s[68:69] nt
	s_add_u32 s68, s68, s70
	s_addc_u32 s69, s69, 0
	global_load_dwordx4 v[212:215], v54, s[68:69] nt
	s_mul_i32 s6, s70, 3
	s_sub_u32 s68, s68, s6
	s_subb_u32 s69, s69, 0
	s_add_u32 s68, s68, 0x200
	s_addc_u32 s69, s69, 0
	global_load_dwordx4 v[216:219], v54, s[68:69] nt
	s_add_u32 s68, s68, s70
	s_addc_u32 s69, s69, 0
	global_load_dwordx4 v[220:223], v54, s[68:69] nt
	s_add_u32 s68, s68, s70
	s_addc_u32 s69, s69, 0
	global_load_dwordx4 v[224:227], v54, s[68:69] nt
	s_add_u32 s68, s68, s70
	s_addc_u32 s69, s69, 0
	global_load_dwordx4 v[228:231], v54, s[68:69] nt
	s_mul_i32 s6, s70, 3
	s_sub_u32 s68, s68, s6
	s_subb_u32 s69, s69, 0
	s_add_u32 s68, s68, 0x200
	s_addc_u32 s69, s69, 0
	s_waitcnt vmcnt(0)

; DEVI unsigned pack2(float a, float b) { f32v2 v = {a, b}; return __builtin_bit_cast(unsigned, __builtin_convertvector(v, bf16v2)); }
; DEVI void lds_barrier() { asm volatile("s_waitcnt lgkmcnt(0)" ::: "memory"); __builtin_amdgcn_s_barrier(); asm volatile("" ::: "memory"); }
; DEVI void tconv_store(const TcPre& R, u16* __restrict__ Wt, int K, int N, int t, float* lds, bool perm) {
;   const int tid = threadIdx.x;
;   const int tnN = N / 128;
;   int tk = t / tnN, tn = t % tnN, k0 = tk * 64, n0 = tn * 128;
;   {
;     float* d = lds + (tid >> 5) * 129 + (tid & 31) * 4;
;     d[0] = R.a[0]; d[1] = R.a[1]; d[2] = R.a[2]; d[3] = R.a[3];
;     d[16 * 129] = R.b[0]; d[16 * 129 + 1] = R.b[1]; d[16 * 129 + 2] = R.b[2]; d[16 * 129 + 3] = R.b[3];
;     d[32 * 129] = R.c[0]; d[32 * 129 + 1] = R.c[1]; d[32 * 129 + 2] = R.c[2]; d[32 * 129 + 3] = R.c[3];
;     d[48 * 129] = R.d[0]; d[48 * 129 + 1] = R.d[1]; d[48 * 129 + 2] = R.d[2]; d[48 * 129 + 3] = R.d[3];
;   }
;   lds_barrier();
;   int n0p = !perm ? n0 : (n0 < DFF ? (n0 / 128) * 256 : ((n0 - DFF) / 128) * 256 + 128);
; #pragma unroll
;   for (int p = 0; p < 2; ++p) {
;     int item = p * 512 + tid, n = item >> 3, kg = item & 7;
;     const float* s = lds + (kg * 8) * 129 + n;
;     uint4 o;
;     o.x = pack2(s[0], s[129]); o.y = pack2(s[2 * 129], s[3 * 129]);
;     o.z = pack2(s[4 * 129], s[5 * 129]); o.w = pack2(s[6 * 129], s[7 * 129]);
;     *(uint4*)(Wt + (size_t)(n0p + n) * K + k0 + kg * 8) = o;
;   }
;   lds_barrier();
; }
; DEVI void deferred_conv(const Params& p, char* smem, const int which) {
;     ...
; #pragma unroll
;     for (int u = 0; u < DQ_GRAB; ++u) {
;       int t = base + u;
;       if (t < thi) {
;         if (t < DQ_WO) tconv_store(R[u], (u16*)(ws + O_WO), 4096, 4096, t, lds, false);
;         else if (t < DQ_WO + DQ_WUP) tconv_store(R[u], (u16*)(ws + O_WUP), 4096, NUP, t - DQ_WO, lds, true);
;         else tconv_store(R[u], (u16*)(ws + O_WDN), DFF, 4096, t - DQ_WO - DQ_WUP, lds, false);
;       }
;     }
.Ldcv1_a_st:
	s_add_u32 s6, s86, 0
	s_mul_i32 s6, s6, 0x2b0000
	s_add_u32 s72, s84, s6
	s_addc_u32 s73, s85, 0
	s_add_u32 s78, s72, 0x158000
	s_addc_u32 s79, s73, 0
	s_waitcnt vmcnt(20)
	ds_write2_b32 v58, v168, v169 offset1:1
	ds_write2_b32 v58, v170, v171 offset0:2 offset1:3
	ds_write2_b32 v59, v172, v173 offset1:1
	ds_write2_b32 v59, v174, v175 offset0:2 offset1:3
	ds_write2_b32 v60, v176, v177 offset1:1
	ds_write2_b32 v60, v178, v179 offset0:2 offset1:3
	ds_write2_b32 v61, v180, v181 offset1:1
	ds_write2_b32 v61, v182, v183 offset0:2 offset1:3
	global_load_dwordx4 v[168:171], v54, s[68:69] nt
	s_add_u32 s68, s68, s70
	s_addc_u32 s69, s69, 0
	global_load_dwordx4 v[172:175], v54, s[68:69] nt
	s_add_u32 s68, s68, s70
	s_addc_u32 s69, s69, 0
	global_load_dwordx4 v[176:179], v54, s[68:69] nt
	s_add_u32 s68, s68, s70
	s_addc_u32 s69, s69, 0
	global_load_dwordx4 v[180:183], v54, s[68:69] nt
	s_mul_i32 s6, s70, 3
	s_sub_u32 s68, s68, s6
	s_subb_u32 s69, s69, 0
	s_add_u32 s68, s68, 0x200
	s_addc_u32 s69, s69, 0
	s_waitcnt lgkmcnt(0)
	s_barrier
	ds_read2_b32 v[104:105], v66 offset1:129
	ds_read2_b32 v[106:107], v67 offset1:129
	ds_read2_b32 v[108:109], v68 offset1:129
	ds_read2_b32 v[110:111], v69 offset1:129
	ds_read2_b32 v[112:113], v70 offset1:129
	ds_read2_b32 v[114:115], v71 offset1:129
	ds_read2_b32 v[116:117], v72 offset1:129
	ds_read2_b32 v[118:119], v73 offset1:129
	s_waitcnt lgkmcnt(4)
	v_cvt_pk_bf16_f32 v120, v104, v105
	v_cvt_pk_bf16_f32 v121, v106, v107
	v_cvt_pk_bf16_f32 v122, v108, v109
	v_cvt_pk_bf16_f32 v123, v110, v111
	global_store_dwordx4 v57, v[120:123], s[72:73]
	s_waitcnt lgkmcnt(0)
	v_cvt_pk_bf16_f32 v124, v112, v113
	v_cvt_pk_bf16_f32 v125, v114, v115
	v_cvt_pk_bf16_f32 v126, v116, v117
	v_cvt_pk_bf16_f32 v127, v118, v119
	global_store_dwordx4 v57, v[124:127], s[78:79]
	s_add_u32 s6, s86, 1
	s_mul_i32 s6, s6, 0x2b0000
	s_add_u32 s72, s84, s6
	s_addc_u32 s73, s85, 0
	s_add_u32 s78, s72, 0x158000
	s_addc_u32 s79, s73, 0
	s_waitcnt vmcnt(20)
	ds_write2_b32 v62, v184, v185 offset1:1
	ds_write2_b32 v62, v186, v187 offset0:2 offset1:3
	ds_write2_b32 v63, v188, v189 offset1:1
	ds_write2_b32 v63, v190, v191 offset0:2 offset1:3
	ds_write2_b32 v64, v192, v193 offset1:1
	ds_write2_b32 v64, v194, v195 offset0:2 offset1:3
	ds_write2_b32 v65, v196, v197 offset1:1
	ds_write2_b32 v65, v198, v199 offset0:2 offset1:3
	global_load_dwordx4 v[184:187], v54, s[68:69] nt
	s_add_u32 s68, s68, s70
	s_addc_u32 s69, s69, 0
	global_load_dwordx4 v[188:191], v54, s[68:69] nt
	s_add_u32 s68, s68, s70
	s_addc_u32 s69, s69, 0
	global_load_dwordx4 v[192:195], v54, s[68:69] nt
	s_add_u32 s68, s68, s70
	s_addc_u32 s69, s69, 0
	global_load_dwordx4 v[196:199], v54, s[68:69] nt
	s_mul_i32 s6, s70, 3
	s_sub_u32 s68, s68, s6
	s_subb_u32 s69, s69, 0
	s_add_u32 s68, s68, 0x200
	s_addc_u32 s69, s69, 0
	s_waitcnt lgkmcnt(0)
	s_barrier
	ds_read2_b32 v[104:105], v74 offset1:129
	ds_read2_b32 v[106:107], v75 offset1:129
	ds_read2_b32 v[108:109], v76 offset1:129
	ds_read2_b32 v[110:111], v77 offset1:129
	ds_read2_b32 v[112:113], v78 offset1:129
	ds_read2_b32 v[114:115], v79 offset1:129
	ds_read2_b32 v[116:117], v80 offset1:129
	ds_read2_b32 v[118:119], v81 offset1:129
	s_waitcnt lgkmcnt(4)
	v_cvt_pk_bf16_f32 v120, v104, v105
	v_cvt_pk_bf16_f32 v121, v106, v107
	v_cvt_pk_bf16_f32 v122, v108, v109
	v_cvt_pk_bf16_f32 v123, v110, v111
	global_store_dwordx4 v57, v[120:123], s[72:73]
	s_waitcnt lgkmcnt(0)
	v_cvt_pk_bf16_f32 v124, v112, v113
	v_cvt_pk_bf16_f32 v125, v114, v115
	v_cvt_pk_bf16_f32 v126, v116, v117
	v_cvt_pk_bf16_f32 v127, v118, v119
	global_store_dwordx4 v57, v[124:127], s[78:79]
	s_add_u32 s6, s86, 2
	s_mul_i32 s6, s6, 0x2b0000
	s_add_u32 s72, s84, s6
	s_addc_u32 s73, s85, 0
	s_add_u32 s78, s72, 0x158000
	s_addc_u32 s79, s73, 0
	s_waitcnt vmcnt(20)
	ds_write2_b32 v58, v200, v201 offset1:1
	ds_write2_b32 v58, v202, v203 offset0:2 offset1:3
	ds_write2_b32 v59, v204, v205 offset1:1
	ds_write2_b32 v59, v206, v207 offset0:2 offset1:3
	ds_write2_b32 v60, v208, v209 offset1:1
	ds_write2_b32 v60, v210, v211 offset0:2 offset1:3
	ds_write2_b32 v61, v212, v213 offset1:1
	ds_write2_b32 v61, v214, v215 offset0:2 offset1:3
	global_load_dwordx4 v[200:203], v54, s[68:69] nt
	s_add_u32 s68, s68, s70
	s_addc_u32 s69, s69, 0
	global_load_dwordx4 v[204:207], v54, s[68:69] nt
	s_add_u32 s68, s68, s70
	s_addc_u32 s69, s69, 0
	global_load_dwordx4 v[208:211], v54, s[68:69] nt
	s_add_u32 s68, s68, s70
	s_addc_u32 s69, s69, 0
	global_load_dwordx4 v[212:215], v54, s[68:69] nt
	s_mul_i32 s6, s70, 3
	s_sub_u32 s68, s68, s6
	s_subb_u32 s69, s69, 0
	s_add_u32 s68, s68, 0x200
	s_addc_u32 s69, s69, 0
	s_waitcnt lgkmcnt(0)
	s_barrier
	ds_read2_b32 v[104:105], v66 offset1:129
	ds_read2_b32 v[106:107], v67 offset1:129
	ds_read2_b32 v[108:109], v68 offset1:129
	ds_read2_b32 v[110:111], v69 offset1:129
	ds_read2_b32 v[112:113], v70 offset1:129
	ds_read2_b32 v[114:115], v71 offset1:129
	ds_read2_b32 v[116:117], v72 offset1:129
	ds_read2_b32 v[118:119], v73 offset1:129
	s_waitcnt lgkmcnt(4)
	v_cvt_pk_bf16_f32 v120, v104, v105
	v_cvt_pk_bf16_f32 v121, v106, v107
	v_cvt_pk_bf16_f32 v122, v108, v109
	v_cvt_pk_bf16_f32 v123, v110, v111
	global_store_dwordx4 v57, v[120:123], s[72:73]
	s_waitcnt lgkmcnt(0)
	v_cvt_pk_bf16_f32 v124, v112, v113
	v_cvt_pk_bf16_f32 v125, v114, v115
	v_cvt_pk_bf16_f32 v126, v116, v117
	v_cvt_pk_bf16_f32 v127, v118, v119
	global_store_dwordx4 v57, v[124:127], s[78:79]
	s_add_u32 s6, s86, 3
	s_mul_i32 s6, s6, 0x2b0000
	s_add_u32 s72, s84, s6
	s_addc_u32 s73, s85, 0
	s_add_u32 s78, s72, 0x158000
	s_addc_u32 s79, s73, 0
	s_waitcnt vmcnt(20)
	ds_write2_b32 v62, v216, v217 offset1:1
	ds_write2_b32 v62, v218, v219 offset0:2 offset1:3
	ds_write2_b32 v63, v220, v221 offset1:1
	ds_write2_b32 v63, v222, v223 offset0:2 offset1:3
	ds_write2_b32 v64, v224, v225 offset1:1
	ds_write2_b32 v64, v226, v227 offset0:2 offset1:3
	ds_write2_b32 v65, v228, v229 offset1:1
	ds_write2_b32 v65, v230, v231 offset0:2 offset1:3
	global_load_dwordx4 v[216:219], v54, s[68:69] nt
	s_add_u32 s68, s68, s70
	s_addc_u32 s69, s69, 0
	global_load_dwordx4 v[220:223], v54, s[68:69] nt
	s_add_u32 s68, s68, s70
	s_addc_u32 s69, s69, 0
	global_load_dwordx4 v[224:227], v54, s[68:69] nt
	s_add_u32 s68, s68, s70
	s_addc_u32 s69, s69, 0
	global_load_dwordx4 v[228:231], v54, s[68:69] nt
	s_mul_i32 s6, s70, 3
	s_sub_u32 s68, s68, s6
	s_subb_u32 s69, s69, 0
	s_add_u32 s68, s68, 0x200
	s_addc_u32 s69, s69, 0
	s_cmp_lg_u32 s33, 0
	s_cbranch_scc1 .Ldcv1_b_st
	s_mov_b64 exec, 1
	s_waitcnt vmcnt(22)
	ds_write_b32 v84, v52
	s_mov_b64 exec, s[76:77]

; DEVI void lds_barrier() { asm volatile("s_waitcnt lgkmcnt(0)" ::: "memory"); __builtin_amdgcn_s_barrier(); asm volatile("" ::: "memory"); }
; template <int MODE> ...
;     ...
;         const int wbase = (ewr * 64 + efq * 4) * 1024 + (((ewc ^ efq) << 3) << 4) + (efr >> 2) * 16 + (efr & 3) * 4;
; #pragma unroll
;         for (int ai = 0; ai < 2; ++ai) {
;           if (ai) lds_barrier();
; #pragma unroll
;           for (int bj = 0; bj < 2; ++bj)
; #pragma unroll
;             for (int m = 0; m < 4; ++m)
; #pragma unroll
;               for (int n = 0; n < 2; ++n)
; #pragma unroll
;                 for (int j = 0; j < 4; ++j)
;                   *(float*)(ls + wbase + ((m * 16 + j) * 1024 + (bj * 32 + n * 4) * 16)) = acc[ai][bj][m][n][j];
;           lds_barrier();
;           const long gb = (long)(brow + ai * HALF) * ldc + bcol;
; #pragma unroll 8
;           for (int it = 0; it < 16; ++it) {
;             int item = it * 512 + t2, row = item >> 6, q = item & 63;
;             float4 v = *(const float4*)(ls + row * 1024 + ((q ^ (((row >> 2) & 3) << 3)) << 4));
;             long g = gb + (long)row * ldc + q * 4;
;             float4 r = *(const float4*)(resid + g);
;             if (MODE == 4) {
;               float2 st = *(const float2*)(aux0 + 2 * (long)(brow + ai * HALF + row));
;               float4 gg = *(const float4*)(aux1 + bcol + q * 4), bb = *(const float4*)(aux2 + bcol + q * 4);
.LBB0_851:
	s_or_b64 exec, exec, s[60:61]
	v_mov_b32_e32 v138, v164
	s_lshl_b64 s[60:61], s[50:51], 2
	v_lshrrev_b32_e32 v128, 6, v138
	v_lshrrev_b32_e32 v139, 4, v138
	v_xor_b32_e32 v128, v128, v139
	v_lshlrev_b32_e32 v140, 8, v138
	v_lshlrev_b32_e32 v128, 7, v128
	v_lshlrev_b32_e32 v139, 2, v138
	v_and_b32_e32 v128, 0x180, v128
	v_and_b32_e32 v139, 60, v139
	v_and_b32_e32 v140, 0xffff3000, v140
	v_or3_b32 v140, v140, v128, v139
	ds_write2_b32 v140, v120, v124 offset1:16
	v_add_u32_e32 v120, 0x400, v140
	ds_write2_b32 v120, v121, v125 offset1:16
	v_add_u32_e32 v121, 0x800, v140
	ds_write2_b32 v121, v122, v126 offset1:16
	v_add_u32_e32 v122, 0xc00, v140
	ds_write2_b32 v122, v123, v127 offset1:16
	v_add_u32_e32 v123, 0x4000, v140
	ds_write2_b32 v123, v112, v116 offset1:16
	v_add_u32_e32 v112, 0x4400, v140
	ds_write2_b32 v112, v113, v117 offset1:16
	v_add_u32_e32 v113, 0x4800, v140
	ds_write2_b32 v113, v114, v118 offset1:16
	v_add_u32_e32 v114, 0x4c00, v140
	ds_write2_b32 v114, v115, v119 offset1:16
	v_add_u32_e32 v115, 0x8000, v140
	ds_write2_b32 v115, v104, v108 offset1:16
	v_add_u32_e32 v104, 0x8400, v140
	ds_write2_b32 v104, v105, v109 offset1:16
	v_add_u32_e32 v105, 0x8800, v140
	ds_write2_b32 v105, v106, v110 offset1:16
	v_add_u32_e32 v106, 0x8c00, v140
	ds_write2_b32 v106, v107, v111 offset1:16
	v_add_u32_e32 v107, 0xc000, v140
	ds_write2_b32 v107, v64, v84 offset1:16
	v_add_u32_e32 v84, 0xc400, v140
	ds_write2_b32 v84, v65, v85 offset1:16
	v_add_u32_e32 v85, 0xc800, v140
	s_add_u32 s62, s18, s60
	ds_write2_b32 v85, v66, v86 offset1:16
	v_add_u32_e32 v86, 0xcc00, v140
	v_and_b32_e32 v139, 63, v138
	s_addc_u32 s63, s19, s61
	ds_write2_b32 v86, v67, v87 offset1:16
	ds_write2_b32 v140, v68, v88 offset0:128 offset1:144
	ds_write2_b32 v120, v69, v89 offset0:128 offset1:144
	ds_write2_b32 v121, v70, v90 offset0:128 offset1:144
	ds_write2_b32 v122, v71, v91 offset0:128 offset1:144
	ds_write2_b32 v123, v72, v92 offset0:128 offset1:144
	ds_write2_b32 v112, v73, v93 offset0:128 offset1:144
	ds_write2_b32 v113, v74, v94 offset0:128 offset1:144
	ds_write2_b32 v114, v75, v95 offset0:128 offset1:144
	ds_write2_b32 v115, v76, v96 offset0:128 offset1:144
	ds_write2_b32 v104, v77, v97 offset0:128 offset1:144
	ds_write2_b32 v105, v78, v98 offset0:128 offset1:144
	ds_write2_b32 v106, v79, v99 offset0:128 offset1:144
	ds_write2_b32 v107, v80, v100 offset0:128 offset1:144
	ds_write2_b32 v84, v81, v101 offset0:128 offset1:144
	ds_write2_b32 v85, v82, v102 offset0:128 offset1:144
	ds_write2_b32 v86, v83, v103 offset0:128 offset1:144
	v_lshlrev_b32_e32 v128, 4, v139
	s_add_u32 s60, s20, s60
	s_waitcnt lgkmcnt(0)
	s_barrier
	s_addc_u32 s61, s21, s61
	global_load_dwordx4 v[64:67], v128, s[62:63] nt
	global_load_dwordx4 v[68:71], v128, s[60:61] nt
	v_lshrrev_b32_e32 v78, 5, v138
	v_bitop3_b32 v78, v78, v139, 24 bitop3:0x6c
	v_lshl_or_b32 v72, v139, 2, s50
	v_mov_b32_e32 v73, s51
	v_lshl_add_u64 v[76:77], s[62:63], 0, v[128:129]
	v_lshl_add_u64 v[74:75], s[60:61], 0, v[128:129]
	v_lshlrev_b32_e32 v78, 4, v78
	s_mov_b32 s45, 0
.LBB0_852:
	v_add_u32_e32 v79, s45, v138
	v_ashrrev_i32_e32 v80, 6, v79
	v_add_u32_e32 v82, 0x200, v79
	v_add_u32_e32 v83, 0x400, v79
	v_add_u32_e32 v87, 0x600, v79
	v_add_u32_e32 v89, 0x800, v79
	v_add_u32_e32 v91, 0xa00, v79
	v_add_u32_e32 v93, 0xc00, v79
	v_add_u32_e32 v79, 0xe00, v79
	v_ashrrev_i32_e32 v81, 31, v80
	v_add_u32_e32 v88, s48, v80
	v_ashrrev_i32_e32 v90, 6, v83
	v_ashrrev_i32_e32 v96, 6, v93
	v_ashrrev_i32_e32 v110, 6, v79
	v_lshl_or_b32 v97, v80, 10, v78
	v_ashrrev_i32_e32 v100, 6, v82
	v_lshrrev_b32_e32 v98, 5, v82
	v_ashrrev_i32_e32 v102, 6, v87
	v_lshrrev_b32_e32 v87, 5, v87
	v_ashrrev_i32_e32 v92, 6, v89
	v_ashrrev_i32_e32 v108, 6, v91
	v_lshrrev_b32_e32 v99, 5, v91
	v_lshrrev_b32_e32 v79, 5, v79
	v_lshl_add_u64 v[94:95], v[80:81], 0, s[48:49]
	v_ashrrev_i32_e32 v89, 31, v88
	v_lshl_or_b32 v125, v90, 10, v78
	v_ashrrev_i32_e32 v91, 31, v90
	v_add_u32_e32 v144, s48, v96
	v_add_u32_e32 v146, s48, v110
	ds_read_b128 v[80:83], v97
	v_bitop3_b32 v98, v98, v139, 24 bitop3:0x6c
	v_ashrrev_i32_e32 v101, 31, v100
	v_add_u32_e32 v116, s48, v100
	v_add_u32_e32 v118, s48, v90
	v_bitop3_b32 v87, v87, v139, 24 bitop3:0x6c
	v_ashrrev_i32_e32 v103, 31, v102
	v_add_u32_e32 v124, s48, v102
	v_lshl_or_b32 v128, v92, 10, v78
	v_ashrrev_i32_e32 v93, 31, v92
	v_add_u32_e32 v126, s48, v92
	v_bitop3_b32 v99, v99, v139, 24 bitop3:0x6c
	v_ashrrev_i32_e32 v109, 31, v108
	v_bitop3_b32 v79, v79, v139, 24 bitop3:0x6c
	v_ashrrev_i32_e32 v111, 31, v110
	v_lshlrev_b64 v[148:149], 12, v[94:95]
	v_lshl_add_u64 v[170:171], v[88:89], 3, s[12:13]
	v_lshl_add_u64 v[174:175], v[90:91], 0, s[48:49]
	ds_read_b128 v[88:91], v125
	v_ashrrev_i32_e32 v97, 31, v96
	v_ashrrev_i32_e32 v145, 31, v144
	v_ashrrev_i32_e32 v147, 31, v146
	v_add_u32_e32 v142, s48, v108
	v_lshl_or_b32 v141, v96, 10, v78
	v_lshlrev_b32_e32 v169, 4, v98
	v_lshl_add_u64 v[172:173], v[100:101], 0, s[48:49]
	v_ashrrev_i32_e32 v117, 31, v116
	v_ashrrev_i32_e32 v119, 31, v118
	v_lshlrev_b32_e32 v87, 4, v87
	v_lshl_add_u64 v[176:177], v[102:103], 0, s[48:49]
	v_ashrrev_i32_e32 v125, 31, v124
	v_lshl_add_u64 v[178:179], v[92:93], 0, s[48:49]
	v_ashrrev_i32_e32 v127, 31, v126
	ds_read_b128 v[92:95], v128
	v_lshlrev_b32_e32 v128, 4, v99
	v_lshl_add_u64 v[180:181], v[108:109], 0, s[48:49]
	v_lshl_add_u64 v[182:183], v[96:97], 0, s[48:49]
	v_lshlrev_b32_e32 v79, 4, v79
	v_lshl_add_u64 v[184:185], v[110:111], 0, s[48:49]
	v_lshl_add_u64 v[148:149], v[148:149], 0, v[72:73]
	v_lshl_add_u64 v[144:145], v[144:145], 3, s[12:13]
	v_lshl_add_u64 v[146:147], v[146:147], 3, s[12:13]
	v_ashrrev_i32_e32 v143, 31, v142
; template <int MODE> ...
;     ...
; #pragma unroll 8
;           for (int it = 0; it < 16; ++it) {
;             int item = it * 512 + t2, row = item >> 6, q = item & 63;
;             float4 v = *(const float4*)(ls + row * 1024 + ((q ^ (((row >> 2) & 3) << 3)) << 4));
;             long g = gb + (long)row * ldc + q * 4;
;             float4 r = *(const float4*)(resid + g);
;             if (MODE == 4) {
;               float2 st = *(const float2*)(aux0 + 2 * (long)(brow + ai * HALF + row));
;               float4 gg = *(const float4*)(aux1 + bcol + q * 4), bb = *(const float4*)(aux2 + bcol + q * 4);
;               r.x = (r.x - st.x) * st.y * gg.x + bb.x; r.y = (r.y - st.x) * st.y * gg.y + bb.y;
;               r.z = (r.z - st.x) * st.y * gg.z + bb.z; r.w = (r.w - st.x) * st.y * gg.w + bb.w;
;             }
	ds_read_b128 v[96:99], v141
	global_load_dwordx2 v[194:195], v[170:171], off
	global_load_dwordx2 v[208:209], v[144:145], off
	global_load_dwordx2 v[210:211], v[146:147], off
	v_lshl_or_b32 v141, v100, 10, v169
	v_lshlrev_b64 v[100:101], 12, v[172:173]
	v_lshl_add_u64 v[116:117], v[116:117], 3, s[12:13]
	v_lshlrev_b64 v[170:171], 12, v[174:175]
	v_lshl_add_u64 v[118:119], v[118:119], 3, s[12:13]
	v_lshl_or_b32 v87, v102, 10, v87
	v_lshlrev_b64 v[102:103], 12, v[176:177]
	v_lshl_add_u64 v[124:125], v[124:125], 3, s[12:13]
	v_lshlrev_b64 v[172:173], 12, v[178:179]
	v_lshl_add_u64 v[126:127], v[126:127], 3, s[12:13]
	v_lshl_or_b32 v128, v108, 10, v128
	v_lshlrev_b64 v[108:109], 12, v[180:181]
	v_lshlrev_b64 v[174:175], 12, v[182:183]
	v_lshl_or_b32 v79, v110, 10, v79
	v_lshlrev_b64 v[110:111], 12, v[184:185]
	v_lshlrev_b64 v[196:197], 2, v[148:149]
	v_lshl_add_u64 v[142:143], v[142:143], 3, s[12:13]
	v_lshl_add_u64 v[100:101], v[100:101], 0, v[72:73]
	global_load_dwordx2 v[198:199], v[116:117], off
	global_load_dwordx2 v[200:201], v[118:119], off
	global_load_dwordx2 v[202:203], v[124:125], off
	global_load_dwordx2 v[204:205], v[126:127], off
	v_lshl_add_u64 v[116:117], v[170:171], 0, v[72:73]
	v_lshl_add_u64 v[102:103], v[102:103], 0, v[72:73]
	v_lshl_add_u64 v[118:119], v[172:173], 0, v[72:73]
	v_lshl_add_u64 v[108:109], v[108:109], 0, v[72:73]
	v_lshl_add_u64 v[124:125], v[174:175], 0, v[72:73]
	v_lshl_add_u64 v[110:111], v[110:111], 0, v[72:73]
	v_lshl_add_u64 v[126:127], s[10:11], 0, v[196:197]
	global_load_dwordx2 v[206:207], v[142:143], off
	v_lshlrev_b64 v[212:213], 2, v[100:101]
	v_lshlrev_b64 v[214:215], 2, v[116:117]
	v_lshlrev_b64 v[216:217], 2, v[102:103]
	v_lshlrev_b64 v[218:219], 2, v[118:119]
	v_lshlrev_b64 v[220:221], 2, v[108:109]
	v_lshlrev_b64 v[222:223], 2, v[124:125]
	v_lshlrev_b64 v[224:225], 2, v[110:111]
	global_load_dwordx4 v[100:103], v[126:127], off nt
	v_lshl_add_u64 v[108:109], s[10:11], 0, v[212:213]
	v_lshl_add_u64 v[116:117], s[10:11], 0, v[214:215]
	v_lshl_add_u64 v[124:125], s[10:11], 0, v[216:217]
	v_lshl_add_u64 v[142:143], s[10:11], 0, v[218:219]
	v_lshl_add_u64 v[146:147], s[10:11], 0, v[220:221]
	v_lshl_add_u64 v[170:171], s[10:11], 0, v[222:223]
	v_lshl_add_u64 v[174:175], s[10:11], 0, v[224:225]
	global_load_dwordx4 v[108:111], v[108:109], off nt
	s_nop 0
	global_load_dwordx4 v[116:119], v[116:117], off nt
	s_nop 0
	global_load_dwordx4 v[124:127], v[124:125], off nt
	s_nop 0
	global_load_dwordx4 v[142:145], v[142:143], off nt
	s_nop 0
	global_load_dwordx4 v[146:149], v[146:147], off nt
	s_nop 0
	global_load_dwordx4 v[170:173], v[170:171], off nt
	s_nop 0
	global_load_dwordx4 v[174:177], v[174:175], off nt
	ds_read_b128 v[178:181], v141
	ds_read_b128 v[182:185], v87
	ds_read_b128 v[186:189], v128
	ds_read_b128 v[190:193], v79
	s_addk_i32 s45, 0x1000
	v_lshl_add_u64 v[196:197], s[54:55], 0, v[196:197]
	s_cmpk_eq_i32 s45, 0x2000
	v_lshl_add_u64 v[212:213], s[54:55], 0, v[212:213]
	v_lshl_add_u64 v[214:215], s[54:55], 0, v[214:215]
	v_lshl_add_u64 v[216:217], s[54:55], 0, v[216:217]
	v_lshl_add_u64 v[218:219], s[54:55], 0, v[218:219]
	v_lshl_add_u64 v[220:221], s[54:55], 0, v[220:221]
	v_lshl_add_u64 v[222:223], s[54:55], 0, v[222:223]
	v_lshl_add_u64 v[224:225], s[54:55], 0, v[224:225]
	s_waitcnt vmcnt(0)
	v_pk_add_f32 v[100:101], v[100:101], v[194:195] op_sel_hi:[1,0] neg_lo:[0,1] neg_hi:[0,1]
	v_pk_add_f32 v[102:103], v[102:103], v[194:195] op_sel_hi:[1,0] neg_lo:[0,1] neg_hi:[0,1]
	v_pk_mul_f32 v[100:101], v[100:101], v[194:195] op_sel:[0,1]
	v_pk_mul_f32 v[102:103], v[102:103], v[194:195] op_sel:[0,1]
	v_pk_add_f32 v[108:109], v[108:109], v[198:199] op_sel_hi:[1,0] neg_lo:[0,1] neg_hi:[0,1]
	v_pk_add_f32 v[110:111], v[110:111], v[198:199] op_sel_hi:[1,0] neg_lo:[0,1] neg_hi:[0,1]
	v_pk_add_f32 v[116:117], v[116:117], v[200:201] op_sel_hi:[1,0] neg_lo:[0,1] neg_hi:[0,1]
	v_pk_add_f32 v[118:119], v[118:119], v[200:201] op_sel_hi:[1,0] neg_lo:[0,1] neg_hi:[0,1]
	v_pk_add_f32 v[124:125], v[124:125], v[202:203] op_sel_hi:[1,0] neg_lo:[0,1] neg_hi:[0,1]
	v_pk_add_f32 v[126:127], v[126:127], v[202:203] op_sel_hi:[1,0] neg_lo:[0,1] neg_hi:[0,1]
	v_pk_add_f32 v[142:143], v[142:143], v[204:205] op_sel_hi:[1,0] neg_lo:[0,1] neg_hi:[0,1]
	v_pk_add_f32 v[144:145], v[144:145], v[204:205] op_sel_hi:[1,0] neg_lo:[0,1] neg_hi:[0,1]
	v_pk_add_f32 v[146:147], v[146:147], v[206:207] op_sel_hi:[1,0] neg_lo:[0,1] neg_hi:[0,1]
	v_pk_add_f32 v[148:149], v[148:149], v[206:207] op_sel_hi:[1,0] neg_lo:[0,1] neg_hi:[0,1]
	v_pk_add_f32 v[170:171], v[170:171], v[208:209] op_sel_hi:[1,0] neg_lo:[0,1] neg_hi:[0,1]
	v_pk_add_f32 v[172:173], v[172:173], v[208:209] op_sel_hi:[1,0] neg_lo:[0,1] neg_hi:[0,1]
	v_pk_add_f32 v[174:175], v[174:175], v[210:211] op_sel_hi:[1,0] neg_lo:[0,1] neg_hi:[0,1]
	v_pk_add_f32 v[176:177], v[176:177], v[210:211] op_sel_hi:[1,0] neg_lo:[0,1] neg_hi:[0,1]
	v_pk_fma_f32 v[100:101], v[64:65], v[100:101], v[68:69]
	v_pk_fma_f32 v[102:103], v[66:67], v[102:103], v[70:71]
	v_pk_mul_f32 v[108:109], v[108:109], v[198:199] op_sel:[0,1]
	v_pk_mul_f32 v[110:111], v[110:111], v[198:199] op_sel:[0,1]
	v_pk_mul_f32 v[116:117], v[116:117], v[200:201] op_sel:[0,1]
	v_pk_mul_f32 v[118:119], v[118:119], v[200:201] op_sel:[0,1]
	v_pk_mul_f32 v[124:125], v[124:125], v[202:203] op_sel:[0,1]
	v_pk_mul_f32 v[126:127], v[126:127], v[202:203] op_sel:[0,1]
	v_pk_mul_f32 v[142:143], v[142:143], v[204:205] op_sel:[0,1]
	v_pk_mul_f32 v[144:145], v[144:145], v[204:205] op_sel:[0,1]
	v_pk_mul_f32 v[146:147], v[146:147], v[206:207] op_sel:[0,1]
	v_pk_mul_f32 v[148:149], v[148:149], v[206:207] op_sel:[0,1]
	v_pk_mul_f32 v[170:171], v[170:171], v[208:209] op_sel:[0,1]
	v_pk_mul_f32 v[172:173], v[172:173], v[208:209] op_sel:[0,1]
	v_pk_mul_f32 v[174:175], v[174:175], v[210:211] op_sel:[0,1]
	v_pk_mul_f32 v[176:177], v[176:177], v[210:211] op_sel:[0,1]
	s_waitcnt lgkmcnt(7)
; DEVI void lds_barrier() { asm volatile("s_waitcnt lgkmcnt(0)" ::: "memory"); __builtin_amdgcn_s_barrier(); asm volatile("" ::: "memory"); }
; template <int MODE> ...
;     ...
;         for (int ai = 0; ai < 2; ++ai) {
;           if (ai) lds_barrier();
; #pragma unroll
;           for (int bj = 0; bj < 2; ++bj)
; #pragma unroll
;             for (int m = 0; m < 4; ++m)
; #pragma unroll
;               for (int n = 0; n < 2; ++n)
; #pragma unroll
;                 for (int j = 0; j < 4; ++j)
;                   *(float*)(ls + wbase + ((m * 16 + j) * 1024 + (bj * 32 + n * 4) * 16)) = acc[ai][bj][m][n][j];
;           lds_barrier();
;     ...
;               float4 gg = *(const float4*)(aux1 + bcol + q * 4), bb = *(const float4*)(aux2 + bcol + q * 4);
;               r.x = (r.x - st.x) * st.y * gg.x + bb.x; r.y = (r.y - st.x) * st.y * gg.y + bb.y;
;               r.z = (r.z - st.x) * st.y * gg.z + bb.z; r.w = (r.w - st.x) * st.y * gg.w + bb.w;
;             }
;             float4 o; o.x = ALPHA * r.x + v.x; o.y = ALPHA * r.y + v.y; o.z = ALPHA * r.z + v.z; o.w = ALPHA * r.w + v.w;
;             *(float4*)(outf + g) = o;
;           }
	v_pk_fma_f32 v[80:81], v[100:101], s[44:45], v[80:81] op_sel_hi:[1,0,1]
	v_pk_fma_f32 v[82:83], v[102:103], s[44:45], v[82:83] op_sel_hi:[1,0,1]
	v_pk_fma_f32 v[100:101], v[64:65], v[108:109], v[68:69]
	v_pk_fma_f32 v[102:103], v[66:67], v[110:111], v[70:71]
	v_pk_fma_f32 v[108:109], v[64:65], v[116:117], v[68:69]
	v_pk_fma_f32 v[110:111], v[66:67], v[118:119], v[70:71]
	v_pk_fma_f32 v[116:117], v[64:65], v[124:125], v[68:69]
	v_pk_fma_f32 v[118:119], v[66:67], v[126:127], v[70:71]
	v_pk_fma_f32 v[124:125], v[64:65], v[142:143], v[68:69]
	v_pk_fma_f32 v[126:127], v[66:67], v[144:145], v[70:71]
	v_pk_fma_f32 v[142:143], v[64:65], v[146:147], v[68:69]
	v_pk_fma_f32 v[144:145], v[66:67], v[148:149], v[70:71]
	v_pk_fma_f32 v[146:147], v[64:65], v[170:171], v[68:69]
	v_pk_fma_f32 v[148:149], v[66:67], v[172:173], v[70:71]
	v_pk_fma_f32 v[170:171], v[64:65], v[174:175], v[68:69]
	v_pk_fma_f32 v[172:173], v[66:67], v[176:177], v[70:71]
	global_store_dwordx4 v[196:197], v[80:83], off
	s_waitcnt lgkmcnt(6)
	v_pk_fma_f32 v[88:89], v[108:109], s[44:45], v[88:89] op_sel_hi:[1,0,1]
	v_pk_fma_f32 v[90:91], v[110:111], s[44:45], v[90:91] op_sel_hi:[1,0,1]
	s_waitcnt lgkmcnt(3)
	v_pk_fma_f32 v[80:81], v[100:101], s[44:45], v[178:179] op_sel_hi:[1,0,1]
	v_pk_fma_f32 v[82:83], v[102:103], s[44:45], v[180:181] op_sel_hi:[1,0,1]
	s_waitcnt lgkmcnt(2)
	v_pk_fma_f32 v[100:101], v[116:117], s[44:45], v[182:183] op_sel_hi:[1,0,1]
	v_pk_fma_f32 v[102:103], v[118:119], s[44:45], v[184:185] op_sel_hi:[1,0,1]
	v_pk_fma_f32 v[92:93], v[124:125], s[44:45], v[92:93] op_sel_hi:[1,0,1]
	v_pk_fma_f32 v[94:95], v[126:127], s[44:45], v[94:95] op_sel_hi:[1,0,1]
	s_waitcnt lgkmcnt(1)
	v_pk_fma_f32 v[108:109], v[142:143], s[44:45], v[186:187] op_sel_hi:[1,0,1]
	v_pk_fma_f32 v[110:111], v[144:145], s[44:45], v[188:189] op_sel_hi:[1,0,1]
	v_pk_fma_f32 v[96:97], v[146:147], s[44:45], v[96:97] op_sel_hi:[1,0,1]
	v_pk_fma_f32 v[98:99], v[148:149], s[44:45], v[98:99] op_sel_hi:[1,0,1]
	s_waitcnt lgkmcnt(0)
	v_pk_fma_f32 v[116:117], v[170:171], s[44:45], v[190:191] op_sel_hi:[1,0,1]
	v_pk_fma_f32 v[118:119], v[172:173], s[44:45], v[192:193] op_sel_hi:[1,0,1]
	global_store_dwordx4 v[212:213], v[80:83], off
	global_store_dwordx4 v[214:215], v[88:91], off
	global_store_dwordx4 v[216:217], v[100:103], off
	global_store_dwordx4 v[218:219], v[92:95], off
	global_store_dwordx4 v[220:221], v[108:111], off
	global_store_dwordx4 v[222:223], v[96:99], off
	global_store_dwordx4 v[224:225], v[116:119], off
	s_cbranch_scc0 .LBB0_852
	s_waitcnt lgkmcnt(0)
	s_barrier
	ds_write2_b32 v140, v0, v32 offset1:16
	ds_write2_b32 v120, v1, v33 offset1:16
	ds_write2_b32 v121, v2, v34 offset1:16
	ds_write2_b32 v122, v3, v35 offset1:16
	ds_write2_b32 v123, v4, v36 offset1:16
	ds_write2_b32 v112, v5, v37 offset1:16
	ds_write2_b32 v113, v6, v38 offset1:16
	ds_write2_b32 v114, v7, v39 offset1:16
	ds_write2_b32 v115, v8, v40 offset1:16
	ds_write2_b32 v104, v9, v41 offset1:16
	ds_write2_b32 v105, v10, v42 offset1:16
	ds_write2_b32 v106, v11, v43 offset1:16
	ds_write2_b32 v107, v12, v44 offset1:16
	ds_write2_b32 v84, v13, v45 offset1:16
	ds_write2_b32 v85, v14, v46 offset1:16
	ds_write2_b32 v86, v15, v47 offset1:16
	ds_write2_b32 v140, v16, v48 offset0:128 offset1:144
	ds_write2_b32 v120, v17, v49 offset0:128 offset1:144
	ds_write2_b32 v121, v18, v50 offset0:128 offset1:144
	ds_write2_b32 v122, v19, v51 offset0:128 offset1:144
	ds_write2_b32 v123, v20, v52 offset0:128 offset1:144
	ds_write2_b32 v112, v21, v53 offset0:128 offset1:144
	ds_write2_b32 v113, v22, v54 offset0:128 offset1:144
	ds_write2_b32 v114, v23, v55 offset0:128 offset1:144
	ds_write2_b32 v115, v24, v56 offset0:128 offset1:144
	ds_write2_b32 v104, v25, v57 offset0:128 offset1:144
	ds_write2_b32 v105, v26, v58 offset0:128 offset1:144
	ds_write2_b32 v106, v27, v59 offset0:128 offset1:144
	ds_write2_b32 v107, v28, v60 offset0:128 offset1:144
	ds_write2_b32 v84, v29, v61 offset0:128 offset1:144
	ds_write2_b32 v85, v30, v62 offset0:128 offset1:144
	ds_write2_b32 v86, v31, v63 offset0:128 offset1:144
	s_waitcnt lgkmcnt(0)
	s_barrier
	global_load_dwordx4 v[0:3], v[76:77], off nt
	global_load_dwordx4 v[4:7], v[74:75], off nt
	s_mov_b32 s45, 0
.LBB0_854:
	v_add_u32_e32 v9, s45, v138
	v_ashrrev_i32_e32 v8, 6, v9
	v_add_u32_e32 v11, 0x400, v9
	v_add_u32_e32 v10, 0x200, v9
	v_add_u32_e32 v13, 0x600, v9
	v_add_u32_e32 v15, 0x800, v9
	v_add_u32_e32 v17, 0xa00, v9
	v_add_u32_e32 v18, 0xc00, v9
	v_add_u32_e32 v19, 0xe00, v9
	v_add_u32_e32 v12, s46, v8
	v_ashrrev_i32_e32 v14, 6, v11
	v_lshl_or_b32 v21, v8, 10, v78
	v_ashrrev_i32_e32 v9, 31, v8
	v_lshrrev_b32_e32 v22, 5, v10
	v_ashrrev_i32_e32 v26, 6, v13
	v_lshrrev_b32_e32 v23, 5, v13
	v_ashrrev_i32_e32 v16, 6, v15
	v_lshrrev_b32_e32 v29, 5, v17
	v_ashrrev_i32_e32 v20, 6, v18
	v_ashrrev_i32_e32 v30, 6, v19
	v_ashrrev_i32_e32 v13, 31, v12
	v_lshl_or_b32 v37, v14, 10, v78
	v_ashrrev_i32_e32 v15, 31, v14
	v_ashrrev_i32_e32 v24, 6, v10
	v_ashrrev_i32_e32 v28, 6, v17
	v_lshrrev_b32_e32 v31, 5, v19
	v_lshl_add_u64 v[18:19], v[8:9], 0, s[46:47]
	ds_read_b128 v[8:11], v21
	v_bitop3_b32 v22, v22, v139, 24 bitop3:0x6c
	v_add_u32_e32 v34, s46, v14
	v_bitop3_b32 v23, v23, v139, 24 bitop3:0x6c
	v_lshl_or_b32 v41, v16, 10, v78
	v_ashrrev_i32_e32 v17, 31, v16
	v_bitop3_b32 v43, v29, v139, 24 bitop3:0x6c
	v_lshl_or_b32 v45, v20, 10, v78
	v_add_u32_e32 v42, s46, v20
	v_add_u32_e32 v44, s46, v30
	v_lshl_add_u64 v[48:49], v[12:13], 3, s[12:13]
	v_lshl_add_u64 v[52:53], v[14:15], 0, s[46:47]
	ds_read_b128 v[12:15], v37
	v_ashrrev_i32_e32 v21, 31, v20
	v_ashrrev_i32_e32 v25, 31, v24
	v_add_u32_e32 v32, s46, v24
	v_ashrrev_i32_e32 v27, 31, v26
; template <int MODE> ...
;     ...
; #pragma unroll 8
;           for (int it = 0; it < 16; ++it) {
;             int item = it * 512 + t2, row = item >> 6, q = item & 63;
;             float4 v = *(const float4*)(ls + row * 1024 + ((q ^ (((row >> 2) & 3) << 3)) << 4));
;             long g = gb + (long)row * ldc + q * 4;
;             float4 r = *(const float4*)(resid + g);
;             if (MODE == 4) {
;               float2 st = *(const float2*)(aux0 + 2 * (long)(brow + ai * HALF + row));
;               float4 gg = *(const float4*)(aux1 + bcol + q * 4), bb = *(const float4*)(aux2 + bcol + q * 4);
;               r.x = (r.x - st.x) * st.y * gg.x + bb.x; r.y = (r.y - st.x) * st.y * gg.y + bb.y;
;               r.z = (r.z - st.x) * st.y * gg.z + bb.z; r.w = (r.w - st.x) * st.y * gg.w + bb.w;
;             }
	v_add_u32_e32 v36, s46, v26
	v_add_u32_e32 v38, s46, v16
	v_ashrrev_i32_e32 v29, 31, v28
	v_bitop3_b32 v62, v31, v139, 24 bitop3:0x6c
	v_ashrrev_i32_e32 v31, 31, v30
	v_lshlrev_b64 v[46:47], 12, v[18:19]
	v_lshlrev_b32_e32 v64, 4, v22
	v_lshlrev_b32_e32 v65, 4, v23
	v_lshl_add_u64 v[56:57], v[16:17], 0, s[46:47]
	ds_read_b128 v[16:19], v41
	v_lshlrev_b32_e32 v66, 4, v43
	v_lshl_add_u64 v[60:61], v[20:21], 0, s[46:47]
	v_ashrrev_i32_e32 v43, 31, v42
	ds_read_b128 v[20:23], v45
	v_ashrrev_i32_e32 v45, 31, v44
	v_add_u32_e32 v40, s46, v28
	v_lshl_add_u64 v[50:51], v[24:25], 0, s[46:47]
	v_ashrrev_i32_e32 v33, 31, v32
	v_ashrrev_i32_e32 v35, 31, v34
	v_lshl_add_u64 v[54:55], v[26:27], 0, s[46:47]
	v_ashrrev_i32_e32 v37, 31, v36
	v_ashrrev_i32_e32 v39, 31, v38
	v_lshl_add_u64 v[58:59], v[28:29], 0, s[46:47]
	v_lshlrev_b32_e32 v67, 4, v62
	v_lshl_add_u64 v[62:63], v[30:31], 0, s[46:47]
	v_lshl_add_u64 v[46:47], v[46:47], 0, v[72:73]
	v_lshl_add_u64 v[42:43], v[42:43], 3, s[12:13]
	v_lshl_add_u64 v[44:45], v[44:45], 3, s[12:13]
	v_ashrrev_i32_e32 v41, 31, v40
	global_load_dwordx2 v[74:75], v[48:49], off
	global_load_dwordx2 v[90:91], v[42:43], off
	global_load_dwordx2 v[92:93], v[44:45], off
	v_lshl_or_b32 v64, v24, 10, v64
	v_lshlrev_b64 v[24:25], 12, v[50:51]
	v_lshl_add_u64 v[32:33], v[32:33], 3, s[12:13]
	v_lshlrev_b64 v[48:49], 12, v[52:53]
	v_lshl_add_u64 v[34:35], v[34:35], 3, s[12:13]
	v_lshl_or_b32 v65, v26, 10, v65
	v_lshlrev_b64 v[26:27], 12, v[54:55]
	v_lshl_add_u64 v[36:37], v[36:37], 3, s[12:13]
	v_lshlrev_b64 v[50:51], 12, v[56:57]
	v_lshl_add_u64 v[38:39], v[38:39], 3, s[12:13]
	v_lshl_or_b32 v66, v28, 10, v66
	v_lshlrev_b64 v[28:29], 12, v[58:59]
	v_lshlrev_b64 v[52:53], 12, v[60:61]
	v_lshl_or_b32 v68, v30, 10, v67
	v_lshlrev_b64 v[30:31], 12, v[62:63]
	v_lshlrev_b64 v[76:77], 2, v[46:47]
	v_lshl_add_u64 v[40:41], v[40:41], 3, s[12:13]
	v_lshl_add_u64 v[24:25], v[24:25], 0, v[72:73]
	global_load_dwordx2 v[80:81], v[32:33], off
	global_load_dwordx2 v[82:83], v[34:35], off
	global_load_dwordx2 v[84:85], v[36:37], off
	global_load_dwordx2 v[86:87], v[38:39], off
	v_lshl_add_u64 v[32:33], v[48:49], 0, v[72:73]
	v_lshl_add_u64 v[26:27], v[26:27], 0, v[72:73]
	v_lshl_add_u64 v[34:35], v[50:51], 0, v[72:73]
	v_lshl_add_u64 v[28:29], v[28:29], 0, v[72:73]
	v_lshl_add_u64 v[36:37], v[52:53], 0, v[72:73]
	v_lshl_add_u64 v[30:31], v[30:31], 0, v[72:73]
	v_lshl_add_u64 v[38:39], s[10:11], 0, v[76:77]
	global_load_dwordx2 v[88:89], v[40:41], off
	v_lshlrev_b64 v[94:95], 2, v[24:25]
	v_lshlrev_b64 v[96:97], 2, v[32:33]
	v_lshlrev_b64 v[98:99], 2, v[26:27]
	v_lshlrev_b64 v[100:101], 2, v[34:35]
	v_lshlrev_b64 v[102:103], 2, v[28:29]
	v_lshlrev_b64 v[104:105], 2, v[36:37]
	v_lshlrev_b64 v[106:107], 2, v[30:31]
	global_load_dwordx4 v[24:27], v[38:39], off nt
	v_lshl_add_u64 v[28:29], s[10:11], 0, v[94:95]
	v_lshl_add_u64 v[32:33], s[10:11], 0, v[96:97]
	v_lshl_add_u64 v[36:37], s[10:11], 0, v[98:99]
	v_lshl_add_u64 v[40:41], s[10:11], 0, v[100:101]
	v_lshl_add_u64 v[44:45], s[10:11], 0, v[102:103]
	v_lshl_add_u64 v[48:49], s[10:11], 0, v[104:105]
	v_lshl_add_u64 v[52:53], s[10:11], 0, v[106:107]
	global_load_dwordx4 v[28:31], v[28:29], off nt
	s_nop 0
	global_load_dwordx4 v[32:35], v[32:33], off nt
	s_nop 0
	global_load_dwordx4 v[36:39], v[36:37], off nt
	s_nop 0
	global_load_dwordx4 v[40:43], v[40:41], off nt
	s_nop 0
	global_load_dwordx4 v[44:47], v[44:45], off nt
	s_nop 0
	global_load_dwordx4 v[48:51], v[48:49], off nt
	s_nop 0
	global_load_dwordx4 v[52:55], v[52:53], off nt
	ds_read_b128 v[56:59], v64
	ds_read_b128 v[60:63], v65
	ds_read_b128 v[64:67], v66
	ds_read_b128 v[68:71], v68
	s_addk_i32 s45, 0x1000
	v_lshl_add_u64 v[76:77], s[54:55], 0, v[76:77]
	s_cmpk_lg_i32 s45, 0x2000
	v_lshl_add_u64 v[94:95], s[54:55], 0, v[94:95]
	v_lshl_add_u64 v[96:97], s[54:55], 0, v[96:97]
	v_lshl_add_u64 v[98:99], s[54:55], 0, v[98:99]
	v_lshl_add_u64 v[100:101], s[54:55], 0, v[100:101]
	v_lshl_add_u64 v[102:103], s[54:55], 0, v[102:103]
	v_lshl_add_u64 v[104:105], s[54:55], 0, v[104:105]
	v_lshl_add_u64 v[106:107], s[54:55], 0, v[106:107]
	s_waitcnt vmcnt(7)
	v_pk_add_f32 v[24:25], v[24:25], v[74:75] op_sel_hi:[1,0] neg_lo:[0,1] neg_hi:[0,1]
	v_pk_add_f32 v[26:27], v[26:27], v[74:75] op_sel_hi:[1,0] neg_lo:[0,1] neg_hi:[0,1]
	v_pk_mul_f32 v[24:25], v[24:25], v[74:75] op_sel:[0,1]
	v_pk_mul_f32 v[26:27], v[26:27], v[74:75] op_sel:[0,1]
	s_waitcnt vmcnt(6)
	v_pk_add_f32 v[28:29], v[28:29], v[80:81] op_sel_hi:[1,0] neg_lo:[0,1] neg_hi:[0,1]
	v_pk_add_f32 v[30:31], v[30:31], v[80:81] op_sel_hi:[1,0] neg_lo:[0,1] neg_hi:[0,1]
	s_waitcnt vmcnt(5)
; DEVI void lds_barrier() { asm volatile("s_waitcnt lgkmcnt(0)" ::: "memory"); __builtin_amdgcn_s_barrier(); asm volatile("" ::: "memory"); }
; template <int MODE> ...
;     ...
;               r.x = (r.x - st.x) * st.y * gg.x + bb.x; r.y = (r.y - st.x) * st.y * gg.y + bb.y;
;               r.z = (r.z - st.x) * st.y * gg.z + bb.z; r.w = (r.w - st.x) * st.y * gg.w + bb.w;
;             }
;             float4 o; o.x = ALPHA * r.x + v.x; o.y = ALPHA * r.y + v.y; o.z = ALPHA * r.z + v.z; o.w = ALPHA * r.w + v.w;
;             *(float4*)(outf + g) = o;
;           }
;         }
;       }
;     }
;     lds_barrier();
;   }
	v_pk_add_f32 v[32:33], v[32:33], v[82:83] op_sel_hi:[1,0] neg_lo:[0,1] neg_hi:[0,1]
	v_pk_add_f32 v[34:35], v[34:35], v[82:83] op_sel_hi:[1,0] neg_lo:[0,1] neg_hi:[0,1]
	s_waitcnt vmcnt(4)
	v_pk_add_f32 v[36:37], v[36:37], v[84:85] op_sel_hi:[1,0] neg_lo:[0,1] neg_hi:[0,1]
	v_pk_add_f32 v[38:39], v[38:39], v[84:85] op_sel_hi:[1,0] neg_lo:[0,1] neg_hi:[0,1]
	s_waitcnt vmcnt(3)
	v_pk_add_f32 v[40:41], v[40:41], v[86:87] op_sel_hi:[1,0] neg_lo:[0,1] neg_hi:[0,1]
	v_pk_add_f32 v[42:43], v[42:43], v[86:87] op_sel_hi:[1,0] neg_lo:[0,1] neg_hi:[0,1]
	s_waitcnt vmcnt(2)
	v_pk_add_f32 v[44:45], v[44:45], v[88:89] op_sel_hi:[1,0] neg_lo:[0,1] neg_hi:[0,1]
	v_pk_add_f32 v[46:47], v[46:47], v[88:89] op_sel_hi:[1,0] neg_lo:[0,1] neg_hi:[0,1]
	s_waitcnt vmcnt(1)
	v_pk_add_f32 v[48:49], v[48:49], v[90:91] op_sel_hi:[1,0] neg_lo:[0,1] neg_hi:[0,1]
	v_pk_add_f32 v[50:51], v[50:51], v[90:91] op_sel_hi:[1,0] neg_lo:[0,1] neg_hi:[0,1]
	s_waitcnt vmcnt(0)
	v_pk_add_f32 v[52:53], v[52:53], v[92:93] op_sel_hi:[1,0] neg_lo:[0,1] neg_hi:[0,1]
	v_pk_add_f32 v[54:55], v[54:55], v[92:93] op_sel_hi:[1,0] neg_lo:[0,1] neg_hi:[0,1]
	v_pk_fma_f32 v[24:25], v[0:1], v[24:25], v[4:5]
	v_pk_fma_f32 v[26:27], v[2:3], v[26:27], v[6:7]
	v_pk_mul_f32 v[28:29], v[28:29], v[80:81] op_sel:[0,1]
	v_pk_mul_f32 v[30:31], v[30:31], v[80:81] op_sel:[0,1]
	v_pk_mul_f32 v[32:33], v[32:33], v[82:83] op_sel:[0,1]
	v_pk_mul_f32 v[34:35], v[34:35], v[82:83] op_sel:[0,1]
	v_pk_mul_f32 v[36:37], v[36:37], v[84:85] op_sel:[0,1]
	v_pk_mul_f32 v[38:39], v[38:39], v[84:85] op_sel:[0,1]
	v_pk_mul_f32 v[40:41], v[40:41], v[86:87] op_sel:[0,1]
	v_pk_mul_f32 v[42:43], v[42:43], v[86:87] op_sel:[0,1]
	v_pk_mul_f32 v[44:45], v[44:45], v[88:89] op_sel:[0,1]
	v_pk_mul_f32 v[46:47], v[46:47], v[88:89] op_sel:[0,1]
	v_pk_mul_f32 v[48:49], v[48:49], v[90:91] op_sel:[0,1]
	v_pk_mul_f32 v[50:51], v[50:51], v[90:91] op_sel:[0,1]
	v_pk_mul_f32 v[52:53], v[52:53], v[92:93] op_sel:[0,1]
	v_pk_mul_f32 v[54:55], v[54:55], v[92:93] op_sel:[0,1]
	s_waitcnt lgkmcnt(7)
	v_pk_fma_f32 v[8:9], v[24:25], s[44:45], v[8:9] op_sel_hi:[1,0,1]
	v_pk_fma_f32 v[10:11], v[26:27], s[44:45], v[10:11] op_sel_hi:[1,0,1]
	v_pk_fma_f32 v[24:25], v[0:1], v[28:29], v[4:5]
	v_pk_fma_f32 v[26:27], v[2:3], v[30:31], v[6:7]
	v_pk_fma_f32 v[28:29], v[0:1], v[32:33], v[4:5]
	v_pk_fma_f32 v[30:31], v[2:3], v[34:35], v[6:7]
	v_pk_fma_f32 v[32:33], v[0:1], v[36:37], v[4:5]
	v_pk_fma_f32 v[34:35], v[2:3], v[38:39], v[6:7]
	v_pk_fma_f32 v[36:37], v[0:1], v[40:41], v[4:5]
	v_pk_fma_f32 v[38:39], v[2:3], v[42:43], v[6:7]
	v_pk_fma_f32 v[40:41], v[0:1], v[44:45], v[4:5]
	v_pk_fma_f32 v[42:43], v[2:3], v[46:47], v[6:7]
	v_pk_fma_f32 v[44:45], v[0:1], v[48:49], v[4:5]
	v_pk_fma_f32 v[46:47], v[2:3], v[50:51], v[6:7]
	v_pk_fma_f32 v[48:49], v[0:1], v[52:53], v[4:5]
	v_pk_fma_f32 v[50:51], v[2:3], v[54:55], v[6:7]
	global_store_dwordx4 v[76:77], v[8:11], off
	s_waitcnt lgkmcnt(6)
	v_pk_fma_f32 v[12:13], v[28:29], s[44:45], v[12:13] op_sel_hi:[1,0,1]
	v_pk_fma_f32 v[14:15], v[30:31], s[44:45], v[14:15] op_sel_hi:[1,0,1]
	s_waitcnt lgkmcnt(3)
	v_pk_fma_f32 v[8:9], v[24:25], s[44:45], v[56:57] op_sel_hi:[1,0,1]
	v_pk_fma_f32 v[10:11], v[26:27], s[44:45], v[58:59] op_sel_hi:[1,0,1]
	s_waitcnt lgkmcnt(2)
	v_pk_fma_f32 v[24:25], v[32:33], s[44:45], v[60:61] op_sel_hi:[1,0,1]
	v_pk_fma_f32 v[26:27], v[34:35], s[44:45], v[62:63] op_sel_hi:[1,0,1]
	v_pk_fma_f32 v[16:17], v[36:37], s[44:45], v[16:17] op_sel_hi:[1,0,1]
	v_pk_fma_f32 v[18:19], v[38:39], s[44:45], v[18:19] op_sel_hi:[1,0,1]
	s_waitcnt lgkmcnt(1)
	v_pk_fma_f32 v[28:29], v[40:41], s[44:45], v[64:65] op_sel_hi:[1,0,1]
	v_pk_fma_f32 v[30:31], v[42:43], s[44:45], v[66:67] op_sel_hi:[1,0,1]
	v_pk_fma_f32 v[20:21], v[44:45], s[44:45], v[20:21] op_sel_hi:[1,0,1]
	v_pk_fma_f32 v[22:23], v[46:47], s[44:45], v[22:23] op_sel_hi:[1,0,1]
	s_waitcnt lgkmcnt(0)
	v_pk_fma_f32 v[32:33], v[48:49], s[44:45], v[68:69] op_sel_hi:[1,0,1]
	v_pk_fma_f32 v[34:35], v[50:51], s[44:45], v[70:71] op_sel_hi:[1,0,1]
	global_store_dwordx4 v[94:95], v[8:11], off
	global_store_dwordx4 v[96:97], v[12:15], off
	global_store_dwordx4 v[98:99], v[24:27], off
	global_store_dwordx4 v[100:101], v[16:19], off
	global_store_dwordx4 v[102:103], v[28:31], off
	global_store_dwordx4 v[104:105], v[20:23], off
	global_store_dwordx4 v[106:107], v[32:35], off
	s_cbranch_scc1 .LBB0_854
	s_waitcnt lgkmcnt(0)
	s_barrier
	s_add_i32 s35, s35, s14
	s_cmpk_gt_i32 s35, 0x1ff
	s_cbranch_scc0 .LBB0_841
